# FFN-up phases 7/15: XCD-balanced patch order (352 tiles per XCD), half-patch round unswapped so each CU gets 11 tiles
# speedup vs baseline: 1.0144x; 1.0144x over previous
.Lpmxa_hi:
	s_add_i32 s9, s8, 0xffffffd8
	s_mov_b32 s4, 5
	s_lshr_b32 s5, s13, 2
	s_lshr_b32 s6, s13, 5
	s_xor_b32 s5, s5, s6
	s_and_b32 s5, s5, 1
	s_mul_i32 s5, s5, 36
	s_xor_b32 s13, s13, s5
	s_lshl_b32 s14, s13, 5
